# attention loops: max tree via 16 v_max3 (drop 42 canonicalizing ops), negm rebuild 16 cndmask -> uniform branch
# speedup vs baseline: 1.0098x; 1.0098x over previous
.LBB0_625:
	ds_read_b128 v[166:169], v84 offset:64
	ds_read_b128 v[170:173], v84 offset:96
	ds_read_b128 v[178:181], v84 offset:4672
	ds_read_b128 v[182:185], v84 offset:4704
	s_add_i32 s16, s91, s87
	s_add_i32 s4, s16, 64
	s_cmpk_lt_i32 s4, 0xff42
	s_cselect_b64 vcc, -1, 0
	s_cmpk_gt_i32 s4, 0x9e
	s_cselect_b64 s[4:5], -1, 0
	v_cndmask_b32_e64 v84, 0, v160, s[4:5]
	v_cndmask_b32_e32 v165, v84, v159, vcc
	v_sub_f32_e32 v84, v165, v156
	v_cmp_neq_f32_e64 s[4:5], v165, v142
	s_addk_i32 s16, 0xffa1
	s_cmp_lt_u32 s16, 0xfffffea3
	s_mov_b64 vcc, s[4:5]
	s_cbranch_vccz .Lattn_negm_keep_0
	v_mov_b32_e32 v79, v84
	v_mov_b32_e32 v78, v84
	v_mov_b32_e32 v77, v84
	v_mov_b32_e32 v76, v84
	v_mov_b32_e32 v75, v84
	v_mov_b32_e32 v74, v84
	v_mov_b32_e32 v73, v84
	v_mov_b32_e32 v72, v84
	v_mov_b32_e32 v71, v84
	v_mov_b32_e32 v70, v84
	v_mov_b32_e32 v69, v84
	v_mov_b32_e32 v68, v84
	v_mov_b32_e32 v67, v84
	v_mov_b32_e32 v66, v84
	v_mov_b32_e32 v65, v84
	v_mov_b32_e32 v64, v84
.Lattn_negm_keep_0:
	s_waitcnt lgkmcnt(0)
	s_nop 0
	v_mfma_f32_32x32x16_bf16 v[96:111], v[80:83], v[112:115], v[64:79]
	v_mfma_f32_32x32x16_bf16 v[80:95], v[136:139], v[112:115], v[64:79]
	v_mfma_f32_32x32x16_bf16 v[96:111], v[128:131], v[116:119], v[96:111]
	v_mfma_f32_32x32x16_bf16 v[80:95], v[132:135], v[116:119], v[80:95]
	v_mfma_f32_32x32x16_bf16 v[96:111], v[166:169], v[120:123], v[96:111]
	v_mfma_f32_32x32x16_bf16 v[80:95], v[178:181], v[120:123], v[80:95]
	v_mfma_f32_32x32x16_bf16 v[96:111], v[170:173], v[124:127], v[96:111]
	v_mfma_f32_32x32x16_bf16 v[80:95], v[182:185], v[124:127], v[80:95]
	s_cbranch_scc1 .LBB0_627
	v_add_u32_e32 v180, s87, v164
	v_max_i32_e32 v130, 0xffffff7f, v180
	v_add_u32_e32 v130, 0x81, v130
	s_add_i32 s80, 0, 0x20000
	v_min_u32_e32 v130, 0x100, v130
	v_lshl_add_u32 v132, v130, 2, s80
	v_max_i32_e32 v130, 0xffffff7e, v180
	v_add_u32_e32 v130, 0x82, v130
	v_max_i32_e32 v138, 0xffffff7b, v180
	v_min_u32_e32 v130, 0x100, v130
	v_add_u32_e32 v138, 0x85, v138
	v_max_i32_e32 v128, 0xffffff80, v180
	v_max_i32_e32 v129, 0xffffff60, v180
	v_max_i32_e32 v131, 0xffffff5f, v180
	v_max_i32_e32 v133, 0xffffff5e, v180
	v_lshl_add_u32 v134, v130, 2, s80
	v_max_i32_e32 v130, 0xffffff7d, v180
	v_max_i32_e32 v135, 0xffffff5d, v180
	v_min_u32_e32 v138, 0x100, v138
	v_add_u32_e32 v128, 0x80, v128
	v_add_u32_e32 v129, 0xa0, v129
	v_add_u32_e32 v131, 0xa1, v131
	v_add_u32_e32 v133, 0xa2, v133
	v_add_u32_e32 v130, 0x83, v130
	v_add_u32_e32 v135, 0xa3, v135
	v_lshl_add_u32 v166, v138, 2, s80
	v_max_i32_e32 v138, 0xffffff7a, v180
	v_min_u32_e32 v128, 0x100, v128
	v_min_u32_e32 v129, 0x100, v129
	v_min_u32_e32 v131, 0x100, v131
	v_min_u32_e32 v133, 0x100, v133
	v_min_u32_e32 v130, 0x100, v130
	v_min_u32_e32 v135, 0x100, v135
	v_add_u32_e32 v138, 0x86, v138
	v_max_i32_e32 v172, 0xffffff77, v180
	v_lshl_add_u32 v128, v128, 2, s80
	v_lshl_add_u32 v129, v129, 2, s80
	v_lshl_add_u32 v131, v131, 2, s80
	v_lshl_add_u32 v133, v133, 2, s80
	v_lshl_add_u32 v136, v130, 2, s80
	v_lshl_add_u32 v135, v135, 2, s80
	v_min_u32_e32 v138, 0x100, v138
	v_add_u32_e32 v172, 0x89, v172
	ds_read_b32 v128, v128
	ds_read_b32 v130, v129
	ds_read_b32 v129, v132
	ds_read_b32 v131, v131
	ds_read_b32 v132, v134
	ds_read_b32 v134, v133
	ds_read_b32 v133, v136
	ds_read_b32 v135, v135
	v_max_i32_e32 v136, 0xffffff7c, v180
	v_max_i32_e32 v137, 0xffffff5c, v180
	v_max_i32_e32 v139, 0xffffff5b, v180
	v_max_i32_e32 v167, 0xffffff5a, v180
	v_lshl_add_u32 v168, v138, 2, s80
	v_max_i32_e32 v138, 0xffffff79, v180
	v_max_i32_e32 v169, 0xffffff59, v180
	v_min_u32_e32 v172, 0x100, v172
	v_add_u32_e32 v136, 0x84, v136
	v_add_u32_e32 v137, 0xa4, v137
	v_add_u32_e32 v139, 0xa5, v139
	v_add_u32_e32 v167, 0xa6, v167
	v_add_u32_e32 v138, 0x87, v138
	v_add_u32_e32 v169, 0xa7, v169
	v_lshl_add_u32 v174, v172, 2, s80
	v_max_i32_e32 v172, 0xffffff76, v180
	v_min_u32_e32 v136, 0x100, v136
	v_min_u32_e32 v137, 0x100, v137
	v_min_u32_e32 v139, 0x100, v139
	v_min_u32_e32 v167, 0x100, v167
	v_min_u32_e32 v138, 0x100, v138
	v_min_u32_e32 v169, 0x100, v169
	v_add_u32_e32 v172, 0x8a, v172
	v_lshl_add_u32 v136, v136, 2, s80
	v_lshl_add_u32 v137, v137, 2, s80
	v_lshl_add_u32 v139, v139, 2, s80
	v_lshl_add_u32 v167, v167, 2, s80
	v_lshl_add_u32 v170, v138, 2, s80
	v_lshl_add_u32 v169, v169, 2, s80
	v_min_u32_e32 v172, 0x100, v172
	ds_read_b32 v136, v136
	ds_read_b32 v138, v137
	ds_read_b32 v137, v166
	ds_read_b32 v139, v139
	ds_read_b32 v166, v168
	ds_read_b32 v168, v167
	ds_read_b32 v167, v170
	ds_read_b32 v169, v169
	v_max_i32_e32 v170, 0xffffff78, v180
	v_max_i32_e32 v171, 0xffffff58, v180
	v_max_i32_e32 v173, 0xffffff57, v180
	v_max_i32_e32 v175, 0xffffff56, v180
	v_lshl_add_u32 v178, v172, 2, s80
	v_max_i32_e32 v172, 0xffffff75, v180
	v_max_i32_e32 v179, 0xffffff55, v180
	v_add_u32_e32 v170, 0x88, v170
	v_add_u32_e32 v171, 0xa8, v171
	v_add_u32_e32 v173, 0xa9, v173
	v_add_u32_e32 v175, 0xaa, v175
	v_add_u32_e32 v172, 0x8b, v172
	v_add_u32_e32 v179, 0xab, v179
	v_max_i32_e32 v184, 0xffffff53, v180
	v_max_i32_e32 v185, 0xffffff52, v180
	v_min_u32_e32 v170, 0x100, v170
	v_min_u32_e32 v171, 0x100, v171
	v_min_u32_e32 v173, 0x100, v173
	v_min_u32_e32 v175, 0x100, v175
	v_min_u32_e32 v172, 0x100, v172
	v_min_u32_e32 v179, 0x100, v179
	v_add_u32_e32 v184, 0xad, v184
	v_add_u32_e32 v185, 0xae, v185
	v_lshl_add_u32 v170, v170, 2, s80
	v_lshl_add_u32 v171, v171, 2, s80
	v_lshl_add_u32 v173, v173, 2, s80
	v_lshl_add_u32 v175, v175, 2, s80
	v_lshl_add_u32 v181, v172, 2, s80
	v_lshl_add_u32 v179, v179, 2, s80
	v_min_u32_e32 v184, 0x100, v184
	v_min_u32_e32 v185, 0x100, v185
	ds_read_b32 v170, v170
	ds_read_b32 v172, v171
	ds_read_b32 v171, v174
	ds_read_b32 v173, v173
	ds_read_b32 v174, v178
	ds_read_b32 v178, v175
	ds_read_b32 v175, v181
	ds_read_b32 v179, v179
	v_max_i32_e32 v181, 0xffffff74, v180
	v_max_i32_e32 v182, 0xffffff54, v180
	v_max_i32_e32 v183, 0xffffff73, v180
	v_lshl_add_u32 v188, v184, 2, s80
	v_max_i32_e32 v184, 0xffffff72, v180
	v_lshl_add_u32 v186, v185, 2, s80
	v_max_i32_e32 v185, 0xffffff71, v180
	v_max_i32_e32 v180, 0xffffff51, v180
	v_add_u32_e32 v181, 0x8c, v181
	v_add_u32_e32 v182, 0xac, v182
	v_add_u32_e32 v183, 0x8d, v183
	v_add_u32_e32 v184, 0x8e, v184
	v_add_u32_e32 v185, 0x8f, v185
	v_add_u32_e32 v180, 0xaf, v180
	v_min_u32_e32 v181, 0x100, v181
	v_min_u32_e32 v182, 0x100, v182
	v_min_u32_e32 v183, 0x100, v183
	v_min_u32_e32 v184, 0x100, v184
	v_min_u32_e32 v185, 0x100, v185
	v_min_u32_e32 v180, 0x100, v180
	v_lshl_add_u32 v181, v181, 2, s80
	v_lshl_add_u32 v182, v182, 2, s80
	v_lshl_add_u32 v183, v183, 2, s80
	v_lshl_add_u32 v184, v184, 2, s80
	v_lshl_add_u32 v185, v185, 2, s80
	v_lshl_add_u32 v187, v180, 2, s80
	ds_read_b32 v180, v181
	ds_read_b32 v182, v182
	ds_read_b32 v184, v184
	ds_read_b32 v185, v185
	ds_read_b32 v181, v183
	ds_read_b32 v187, v187
	ds_read_b32 v186, v186
	ds_read_b32 v183, v188
	s_waitcnt lgkmcnt(0)
	v_pk_add_f32 v[110:111], v[110:111], v[184:185]
	v_pk_add_f32 v[108:109], v[108:109], v[180:181]
	v_pk_add_f32 v[106:107], v[106:107], v[174:175]
	v_pk_add_f32 v[104:105], v[104:105], v[170:171]
	v_pk_add_f32 v[102:103], v[102:103], v[166:167]
	v_pk_add_f32 v[100:101], v[100:101], v[136:137]
	v_pk_add_f32 v[98:99], v[98:99], v[132:133]
	v_pk_add_f32 v[96:97], v[96:97], v[128:129]
	v_pk_add_f32 v[94:95], v[94:95], v[186:187]
	v_pk_add_f32 v[92:93], v[92:93], v[182:183]
	v_pk_add_f32 v[90:91], v[90:91], v[178:179]
	v_pk_add_f32 v[88:89], v[88:89], v[172:173]
	v_pk_add_f32 v[86:87], v[86:87], v[168:169]
	v_pk_add_f32 v[84:85], v[84:85], v[138:139]
	v_pk_add_f32 v[82:83], v[82:83], v[134:135]
	v_pk_add_f32 v[80:81], v[80:81], v[130:131]
.LBB0_627:
	s_nop 10
	v_max3_f32 v128, v96, v97, v98
	v_max3_f32 v129, v80, v81, v82
	v_max3_f32 v128, v128, v99, v100
	v_max3_f32 v129, v129, v83, v84
	v_max3_f32 v128, v128, v101, v102
	v_max3_f32 v129, v129, v85, v86
	v_max3_f32 v128, v128, v103, v104
	v_max3_f32 v129, v129, v87, v88
	v_max3_f32 v128, v128, v105, v106
	v_max3_f32 v129, v129, v89, v90
	v_max3_f32 v128, v128, v107, v108
	v_max3_f32 v129, v129, v91, v92
	v_max3_f32 v128, v128, v109, v110
	v_max3_f32 v129, v129, v93, v94
	v_max3_f32 v128, v128, v129, v111
	v_max_f32_e32 v128, v128, v95
	v_mov_b32_e32 v129, v128
	s_nop 1
	v_permlane32_swap_b32_e32 v128, v129
	v_max_f32_e32 v128, v128, v129
	v_cmp_lt_f32_e32 vcc, s96, v128
	s_cbranch_vccz .LBB0_629
	v_max_f32_e32 v64, v128, v128
	v_max_f32_e32 v64, 0, v64
	v_exp_f32_e64 v66, -v64
	v_pk_add_f32 v[96:97], v[96:97], v[64:65] op_sel_hi:[1,0] neg_lo:[0,1] neg_hi:[0,1]
	v_pk_add_f32 v[98:99], v[98:99], v[64:65] op_sel_hi:[1,0] neg_lo:[0,1] neg_hi:[0,1]
	v_pk_add_f32 v[100:101], v[100:101], v[64:65] op_sel_hi:[1,0] neg_lo:[0,1] neg_hi:[0,1]
	v_pk_add_f32 v[102:103], v[102:103], v[64:65] op_sel_hi:[1,0] neg_lo:[0,1] neg_hi:[0,1]
	v_pk_add_f32 v[104:105], v[104:105], v[64:65] op_sel_hi:[1,0] neg_lo:[0,1] neg_hi:[0,1]
	v_pk_add_f32 v[106:107], v[106:107], v[64:65] op_sel_hi:[1,0] neg_lo:[0,1] neg_hi:[0,1]
	v_pk_add_f32 v[108:109], v[108:109], v[64:65] op_sel_hi:[1,0] neg_lo:[0,1] neg_hi:[0,1]
	v_pk_add_f32 v[110:111], v[110:111], v[64:65] op_sel_hi:[1,0] neg_lo:[0,1] neg_hi:[0,1]
	v_mov_b32_e32 v65, v66
	v_sub_f32_e32 v95, v95, v64
	v_sub_f32_e32 v94, v94, v64
	v_sub_f32_e32 v93, v93, v64
	v_sub_f32_e32 v92, v92, v64
	v_sub_f32_e32 v91, v91, v64
	v_sub_f32_e32 v90, v90, v64
	v_sub_f32_e32 v89, v89, v64
	v_sub_f32_e32 v88, v88, v64
	v_sub_f32_e32 v87, v87, v64
	v_sub_f32_e32 v86, v86, v64
	v_sub_f32_e32 v85, v85, v64
	v_sub_f32_e32 v84, v84, v64
	v_sub_f32_e32 v83, v83, v64
	v_sub_f32_e32 v82, v82, v64
	v_sub_f32_e32 v81, v81, v64
	v_sub_f32_e32 v80, v80, v64
	v_pk_mul_f32 v[62:63], v[62:63], v[66:67] op_sel_hi:[1,0]
	v_pk_mul_f32 v[60:61], v[60:61], v[66:67] op_sel_hi:[1,0]
	v_pk_mul_f32 v[58:59], v[58:59], v[66:67] op_sel_hi:[1,0]
	v_pk_mul_f32 v[56:57], v[56:57], v[66:67] op_sel_hi:[1,0]
	v_pk_mul_f32 v[54:55], v[54:55], v[66:67] op_sel_hi:[1,0]
	v_pk_mul_f32 v[52:53], v[52:53], v[66:67] op_sel_hi:[1,0]
	v_pk_mul_f32 v[50:51], v[50:51], v[66:67] op_sel_hi:[1,0]
	v_pk_mul_f32 v[48:49], v[48:49], v[66:67] op_sel_hi:[1,0]
	v_pk_mul_f32 v[14:15], v[14:15], v[66:67] op_sel_hi:[1,0]
	v_pk_mul_f32 v[12:13], v[12:13], v[66:67] op_sel_hi:[1,0]
	v_pk_mul_f32 v[10:11], v[10:11], v[66:67] op_sel_hi:[1,0]
	v_pk_mul_f32 v[8:9], v[8:9], v[66:67] op_sel_hi:[1,0]
	v_pk_mul_f32 v[6:7], v[6:7], v[66:67] op_sel_hi:[1,0]
	v_pk_mul_f32 v[4:5], v[4:5], v[66:67] op_sel_hi:[1,0]
	v_pk_mul_f32 v[2:3], v[2:3], v[66:67] op_sel_hi:[1,0]
	v_pk_mul_f32 v[0:1], v[0:1], v[66:67] op_sel_hi:[1,0]
	v_pk_mul_f32 v[46:47], v[46:47], v[66:67] op_sel_hi:[1,0]
	v_pk_mul_f32 v[44:45], v[44:45], v[66:67] op_sel_hi:[1,0]
	v_pk_mul_f32 v[42:43], v[42:43], v[66:67] op_sel_hi:[1,0]
	v_pk_mul_f32 v[40:41], v[40:41], v[66:67] op_sel_hi:[1,0]
	v_pk_mul_f32 v[38:39], v[38:39], v[66:67] op_sel_hi:[1,0]
	v_pk_mul_f32 v[36:37], v[36:37], v[66:67] op_sel_hi:[1,0]
	v_pk_mul_f32 v[34:35], v[34:35], v[66:67] op_sel_hi:[1,0]
	v_pk_mul_f32 v[32:33], v[32:33], v[66:67] op_sel_hi:[1,0]
	v_pk_mul_f32 v[30:31], v[30:31], v[66:67] op_sel_hi:[1,0]
	v_pk_mul_f32 v[28:29], v[28:29], v[66:67] op_sel_hi:[1,0]
	v_pk_mul_f32 v[26:27], v[26:27], v[66:67] op_sel_hi:[1,0]
	v_pk_mul_f32 v[24:25], v[24:25], v[66:67] op_sel_hi:[1,0]
	v_pk_mul_f32 v[22:23], v[22:23], v[66:67] op_sel_hi:[1,0]
	v_pk_mul_f32 v[20:21], v[20:21], v[66:67] op_sel_hi:[1,0]
	v_pk_mul_f32 v[18:19], v[18:19], v[66:67] op_sel_hi:[1,0]
	v_pk_mul_f32 v[16:17], v[16:17], v[66:67] op_sel_hi:[1,0]
	v_pk_add_f32 v[66:67], v[156:157], v[64:65]
	v_pk_mul_f32 v[64:65], v[156:157], v[64:65]
	s_nop 0
	v_mov_b32_e32 v67, v65
	v_sub_f32_e32 v64, v165, v66
	v_mov_b64_e32 v[156:157], v[66:67]
	v_mov_b32_e32 v65, v64
	v_mov_b32_e32 v66, v64
	v_mov_b32_e32 v67, v64
	v_mov_b32_e32 v68, v64
	v_mov_b32_e32 v69, v64
	v_mov_b32_e32 v70, v64
	v_mov_b32_e32 v71, v64
	v_mov_b32_e32 v72, v64
	v_mov_b32_e32 v73, v64
	v_mov_b32_e32 v74, v64
	v_mov_b32_e32 v75, v64
	v_mov_b32_e32 v76, v64
	v_mov_b32_e32 v77, v64
	v_mov_b32_e32 v78, v64
	v_mov_b32_e32 v79, v64

.LBB0_639:
	s_add_i32 s50, s44, 0
	v_add3_u32 v84, s50, v162, v146
	ds_read_b128 v[80:83], v84
	ds_read_b128 v[128:131], v84 offset:32
	ds_read_b128 v[132:135], v84 offset:4608
	ds_read_b128 v[136:139], v84 offset:4640
	ds_read_b128 v[140:143], v84 offset:64
	ds_read_b128 v[168:171], v84 offset:96
	ds_read_b128 v[172:175], v84 offset:4672
	ds_read_b128 v[178:181], v84 offset:4704
	s_add_i32 s51, s27, s20
	s_add_i32 s4, s51, 64
	s_cmpk_lt_i32 s4, 0xff42
	s_cselect_b64 vcc, -1, 0
	s_cmpk_gt_i32 s4, 0x9e
	s_cselect_b64 s[4:5], -1, 0
	v_cndmask_b32_e64 v84, 0, v160, s[4:5]
	v_cndmask_b32_e32 v167, v84, v159, vcc
	v_sub_f32_e32 v84, v167, v156
	v_cmp_neq_f32_e64 s[4:5], v167, v163
	s_addk_i32 s51, 0xffa1
	s_cmp_lt_u32 s51, 0xfffffea3
	s_mov_b64 vcc, s[4:5]
	s_cbranch_vccz .Lattn_negm_keep_1
	v_mov_b32_e32 v79, v84
	v_mov_b32_e32 v78, v84
	v_mov_b32_e32 v77, v84
	v_mov_b32_e32 v76, v84
	v_mov_b32_e32 v75, v84
	v_mov_b32_e32 v74, v84
	v_mov_b32_e32 v73, v84
	v_mov_b32_e32 v72, v84
	v_mov_b32_e32 v71, v84
	v_mov_b32_e32 v70, v84
	v_mov_b32_e32 v69, v84
	v_mov_b32_e32 v68, v84
	v_mov_b32_e32 v67, v84
	v_mov_b32_e32 v66, v84
	v_mov_b32_e32 v65, v84
	v_mov_b32_e32 v64, v84
.Lattn_negm_keep_1:
	s_waitcnt lgkmcnt(0)
	s_nop 0
	v_mfma_f32_32x32x16_bf16 v[96:111], v[80:83], v[112:115], v[64:79]
	v_mfma_f32_32x32x16_bf16 v[80:95], v[132:135], v[112:115], v[64:79]
	v_mfma_f32_32x32x16_bf16 v[96:111], v[128:131], v[116:119], v[96:111]
	v_mfma_f32_32x32x16_bf16 v[80:95], v[136:139], v[116:119], v[80:95]
	v_mfma_f32_32x32x16_bf16 v[96:111], v[140:143], v[120:123], v[96:111]
	v_mfma_f32_32x32x16_bf16 v[80:95], v[172:175], v[120:123], v[80:95]
	v_mfma_f32_32x32x16_bf16 v[96:111], v[168:171], v[124:127], v[96:111]
	v_mfma_f32_32x32x16_bf16 v[80:95], v[178:181], v[124:127], v[80:95]
	s_cbranch_scc1 .LBB0_641
	v_add_u32_e32 v178, s20, v166
	v_max_i32_e32 v130, 0xffffff7f, v178
	v_add_u32_e32 v130, 0x81, v130
	s_add_i32 s51, 0, 0x20000
	v_min_u32_e32 v130, 0x100, v130
	v_lshl_add_u32 v132, v130, 2, s51
	v_max_i32_e32 v130, 0xffffff7e, v178
	v_add_u32_e32 v130, 0x82, v130
	v_max_i32_e32 v138, 0xffffff7b, v178
	v_min_u32_e32 v130, 0x100, v130
	v_add_u32_e32 v138, 0x85, v138
	v_max_i32_e32 v128, 0xffffff80, v178
	v_max_i32_e32 v129, 0xffffff60, v178
	v_max_i32_e32 v131, 0xffffff5f, v178
	v_max_i32_e32 v133, 0xffffff5e, v178
	v_lshl_add_u32 v134, v130, 2, s51
	v_max_i32_e32 v130, 0xffffff7d, v178
	v_max_i32_e32 v135, 0xffffff5d, v178
	v_min_u32_e32 v138, 0x100, v138
	v_add_u32_e32 v128, 0x80, v128
	v_add_u32_e32 v129, 0xa0, v129
	v_add_u32_e32 v131, 0xa1, v131
	v_add_u32_e32 v133, 0xa2, v133
	v_add_u32_e32 v130, 0x83, v130
	v_add_u32_e32 v135, 0xa3, v135
	v_lshl_add_u32 v140, v138, 2, s51
	v_max_i32_e32 v138, 0xffffff7a, v178
	v_min_u32_e32 v128, 0x100, v128
	v_min_u32_e32 v129, 0x100, v129
	v_min_u32_e32 v131, 0x100, v131
	v_min_u32_e32 v133, 0x100, v133
	v_min_u32_e32 v130, 0x100, v130
	v_min_u32_e32 v135, 0x100, v135
	v_add_u32_e32 v138, 0x86, v138
	v_max_i32_e32 v170, 0xffffff77, v178
	v_lshl_add_u32 v128, v128, 2, s51
	v_lshl_add_u32 v129, v129, 2, s51
	v_lshl_add_u32 v131, v131, 2, s51
	v_lshl_add_u32 v133, v133, 2, s51
	v_lshl_add_u32 v136, v130, 2, s51
	v_lshl_add_u32 v135, v135, 2, s51
	v_min_u32_e32 v138, 0x100, v138
	v_add_u32_e32 v170, 0x89, v170
	ds_read_b32 v128, v128
	ds_read_b32 v130, v129
	ds_read_b32 v129, v132
	ds_read_b32 v131, v131
	ds_read_b32 v132, v134
	ds_read_b32 v134, v133
	ds_read_b32 v133, v136
	ds_read_b32 v135, v135
	v_max_i32_e32 v136, 0xffffff7c, v178
	v_max_i32_e32 v137, 0xffffff5c, v178
	v_max_i32_e32 v139, 0xffffff5b, v178
	v_max_i32_e32 v141, 0xffffff5a, v178
	v_lshl_add_u32 v142, v138, 2, s51
	v_max_i32_e32 v138, 0xffffff79, v178
	v_max_i32_e32 v143, 0xffffff59, v178
	v_min_u32_e32 v170, 0x100, v170
	v_add_u32_e32 v136, 0x84, v136
	v_add_u32_e32 v137, 0xa4, v137
	v_add_u32_e32 v139, 0xa5, v139
	v_add_u32_e32 v141, 0xa6, v141
	v_add_u32_e32 v138, 0x87, v138
	v_add_u32_e32 v143, 0xa7, v143
	v_lshl_add_u32 v172, v170, 2, s51
	v_max_i32_e32 v170, 0xffffff76, v178
	v_min_u32_e32 v136, 0x100, v136
	v_min_u32_e32 v137, 0x100, v137
	v_min_u32_e32 v139, 0x100, v139
	v_min_u32_e32 v141, 0x100, v141
	v_min_u32_e32 v138, 0x100, v138
	v_min_u32_e32 v143, 0x100, v143
	v_add_u32_e32 v170, 0x8a, v170
	v_lshl_add_u32 v136, v136, 2, s51
	v_lshl_add_u32 v137, v137, 2, s51
	v_lshl_add_u32 v139, v139, 2, s51
	v_lshl_add_u32 v141, v141, 2, s51
	v_lshl_add_u32 v168, v138, 2, s51
	v_lshl_add_u32 v143, v143, 2, s51
	v_min_u32_e32 v170, 0x100, v170
	ds_read_b32 v136, v136
	ds_read_b32 v138, v137
	ds_read_b32 v137, v140
	ds_read_b32 v139, v139
	ds_read_b32 v140, v142
	ds_read_b32 v142, v141
	ds_read_b32 v141, v168
	ds_read_b32 v143, v143
	v_max_i32_e32 v168, 0xffffff78, v178
	v_max_i32_e32 v169, 0xffffff58, v178
	v_max_i32_e32 v171, 0xffffff57, v178
	v_max_i32_e32 v173, 0xffffff56, v178
	v_lshl_add_u32 v174, v170, 2, s51
	v_max_i32_e32 v170, 0xffffff75, v178
	v_max_i32_e32 v175, 0xffffff55, v178
	v_add_u32_e32 v168, 0x88, v168
	v_add_u32_e32 v169, 0xa8, v169
	v_add_u32_e32 v171, 0xa9, v171
	v_add_u32_e32 v173, 0xaa, v173
	v_add_u32_e32 v170, 0x8b, v170
	v_add_u32_e32 v175, 0xab, v175
	v_max_i32_e32 v182, 0xffffff53, v178
	v_max_i32_e32 v183, 0xffffff52, v178
	v_min_u32_e32 v168, 0x100, v168
	v_min_u32_e32 v169, 0x100, v169
	v_min_u32_e32 v171, 0x100, v171
	v_min_u32_e32 v173, 0x100, v173
	v_min_u32_e32 v170, 0x100, v170
	v_min_u32_e32 v175, 0x100, v175
	v_add_u32_e32 v182, 0xad, v182
	v_add_u32_e32 v183, 0xae, v183
	v_lshl_add_u32 v168, v168, 2, s51
	v_lshl_add_u32 v169, v169, 2, s51
	v_lshl_add_u32 v171, v171, 2, s51
	v_lshl_add_u32 v173, v173, 2, s51
	v_lshl_add_u32 v179, v170, 2, s51
	v_lshl_add_u32 v175, v175, 2, s51
	v_min_u32_e32 v182, 0x100, v182
	v_min_u32_e32 v183, 0x100, v183
	ds_read_b32 v168, v168
	ds_read_b32 v170, v169
	ds_read_b32 v169, v172
	ds_read_b32 v171, v171
	ds_read_b32 v172, v174
	ds_read_b32 v174, v173
	ds_read_b32 v173, v179
	ds_read_b32 v175, v175
	v_max_i32_e32 v179, 0xffffff74, v178
	v_max_i32_e32 v180, 0xffffff54, v178
	v_max_i32_e32 v181, 0xffffff73, v178
	v_lshl_add_u32 v186, v182, 2, s51
	v_max_i32_e32 v182, 0xffffff72, v178
	v_lshl_add_u32 v184, v183, 2, s51
	v_max_i32_e32 v183, 0xffffff71, v178
	v_max_i32_e32 v178, 0xffffff51, v178
	v_add_u32_e32 v179, 0x8c, v179
	v_add_u32_e32 v180, 0xac, v180
	v_add_u32_e32 v181, 0x8d, v181
	v_add_u32_e32 v182, 0x8e, v182
	v_add_u32_e32 v183, 0x8f, v183
	v_add_u32_e32 v178, 0xaf, v178
	v_min_u32_e32 v179, 0x100, v179
	v_min_u32_e32 v180, 0x100, v180
	v_min_u32_e32 v181, 0x100, v181
	v_min_u32_e32 v182, 0x100, v182
	v_min_u32_e32 v183, 0x100, v183
	v_min_u32_e32 v178, 0x100, v178
	v_lshl_add_u32 v179, v179, 2, s51
	v_lshl_add_u32 v180, v180, 2, s51
	v_lshl_add_u32 v181, v181, 2, s51
	v_lshl_add_u32 v182, v182, 2, s51
	v_lshl_add_u32 v183, v183, 2, s51
	v_lshl_add_u32 v185, v178, 2, s51
	ds_read_b32 v178, v179
	ds_read_b32 v180, v180
	ds_read_b32 v182, v182
	ds_read_b32 v183, v183
	ds_read_b32 v179, v181
	ds_read_b32 v185, v185
	ds_read_b32 v184, v184
	ds_read_b32 v181, v186
	s_waitcnt lgkmcnt(0)
	v_pk_add_f32 v[110:111], v[110:111], v[182:183]
	v_pk_add_f32 v[108:109], v[108:109], v[178:179]
	v_pk_add_f32 v[106:107], v[106:107], v[172:173]
	v_pk_add_f32 v[104:105], v[104:105], v[168:169]
	v_pk_add_f32 v[102:103], v[102:103], v[140:141]
	v_pk_add_f32 v[100:101], v[100:101], v[136:137]
	v_pk_add_f32 v[98:99], v[98:99], v[132:133]
	v_pk_add_f32 v[96:97], v[96:97], v[128:129]
	v_pk_add_f32 v[94:95], v[94:95], v[184:185]
	v_pk_add_f32 v[92:93], v[92:93], v[180:181]
	v_pk_add_f32 v[90:91], v[90:91], v[174:175]
	v_pk_add_f32 v[88:89], v[88:89], v[170:171]
	v_pk_add_f32 v[86:87], v[86:87], v[142:143]
	v_pk_add_f32 v[84:85], v[84:85], v[138:139]
	v_pk_add_f32 v[82:83], v[82:83], v[134:135]
	v_pk_add_f32 v[80:81], v[80:81], v[130:131]
.LBB0_641:
	s_nop 10
	v_max3_f32 v128, v96, v97, v98
	v_max3_f32 v129, v80, v81, v82
	v_max3_f32 v128, v128, v99, v100
	v_max3_f32 v129, v129, v83, v84
	v_max3_f32 v128, v128, v101, v102
	v_max3_f32 v129, v129, v85, v86
	v_max3_f32 v128, v128, v103, v104
	v_max3_f32 v129, v129, v87, v88
	v_max3_f32 v128, v128, v105, v106
	v_max3_f32 v129, v129, v89, v90
	v_max3_f32 v128, v128, v107, v108
	v_max3_f32 v129, v129, v91, v92
	v_max3_f32 v128, v128, v109, v110
	v_max3_f32 v129, v129, v93, v94
	v_max3_f32 v128, v128, v129, v111
	v_max_f32_e32 v128, v128, v95
	v_mov_b32_e32 v129, v128
	s_nop 1
	v_permlane32_swap_b32_e32 v128, v129
	v_max_f32_e32 v128, v128, v129
	v_cmp_lt_f32_e32 vcc, s96, v128
	s_cbranch_vccz .LBB0_643
	v_max_f32_e32 v64, v128, v128
	v_max_f32_e32 v64, 0, v64
	v_exp_f32_e64 v66, -v64
	v_pk_add_f32 v[96:97], v[96:97], v[64:65] op_sel_hi:[1,0] neg_lo:[0,1] neg_hi:[0,1]
	v_pk_add_f32 v[98:99], v[98:99], v[64:65] op_sel_hi:[1,0] neg_lo:[0,1] neg_hi:[0,1]
	v_pk_add_f32 v[100:101], v[100:101], v[64:65] op_sel_hi:[1,0] neg_lo:[0,1] neg_hi:[0,1]
	v_pk_add_f32 v[102:103], v[102:103], v[64:65] op_sel_hi:[1,0] neg_lo:[0,1] neg_hi:[0,1]
	v_pk_add_f32 v[104:105], v[104:105], v[64:65] op_sel_hi:[1,0] neg_lo:[0,1] neg_hi:[0,1]
	v_pk_add_f32 v[106:107], v[106:107], v[64:65] op_sel_hi:[1,0] neg_lo:[0,1] neg_hi:[0,1]
	v_pk_add_f32 v[108:109], v[108:109], v[64:65] op_sel_hi:[1,0] neg_lo:[0,1] neg_hi:[0,1]
	v_pk_add_f32 v[110:111], v[110:111], v[64:65] op_sel_hi:[1,0] neg_lo:[0,1] neg_hi:[0,1]
	v_mov_b32_e32 v65, v66
	v_sub_f32_e32 v95, v95, v64
	v_sub_f32_e32 v94, v94, v64
	v_sub_f32_e32 v93, v93, v64
	v_sub_f32_e32 v92, v92, v64
	v_sub_f32_e32 v91, v91, v64
	v_sub_f32_e32 v90, v90, v64
	v_sub_f32_e32 v89, v89, v64
	v_sub_f32_e32 v88, v88, v64
	v_sub_f32_e32 v87, v87, v64
	v_sub_f32_e32 v86, v86, v64
	v_sub_f32_e32 v85, v85, v64
	v_sub_f32_e32 v84, v84, v64
	v_sub_f32_e32 v83, v83, v64
	v_sub_f32_e32 v82, v82, v64
	v_sub_f32_e32 v81, v81, v64
	v_sub_f32_e32 v80, v80, v64
	v_pk_mul_f32 v[62:63], v[62:63], v[66:67] op_sel_hi:[1,0]
	v_pk_mul_f32 v[60:61], v[60:61], v[66:67] op_sel_hi:[1,0]
	v_pk_mul_f32 v[58:59], v[58:59], v[66:67] op_sel_hi:[1,0]
	v_pk_mul_f32 v[56:57], v[56:57], v[66:67] op_sel_hi:[1,0]
	v_pk_mul_f32 v[54:55], v[54:55], v[66:67] op_sel_hi:[1,0]
	v_pk_mul_f32 v[52:53], v[52:53], v[66:67] op_sel_hi:[1,0]
	v_pk_mul_f32 v[50:51], v[50:51], v[66:67] op_sel_hi:[1,0]
	v_pk_mul_f32 v[48:49], v[48:49], v[66:67] op_sel_hi:[1,0]
	v_pk_mul_f32 v[14:15], v[14:15], v[66:67] op_sel_hi:[1,0]
	v_pk_mul_f32 v[12:13], v[12:13], v[66:67] op_sel_hi:[1,0]
	v_pk_mul_f32 v[10:11], v[10:11], v[66:67] op_sel_hi:[1,0]
	v_pk_mul_f32 v[8:9], v[8:9], v[66:67] op_sel_hi:[1,0]
	v_pk_mul_f32 v[6:7], v[6:7], v[66:67] op_sel_hi:[1,0]
	v_pk_mul_f32 v[4:5], v[4:5], v[66:67] op_sel_hi:[1,0]
	v_pk_mul_f32 v[2:3], v[2:3], v[66:67] op_sel_hi:[1,0]
	v_pk_mul_f32 v[0:1], v[0:1], v[66:67] op_sel_hi:[1,0]
	v_pk_mul_f32 v[46:47], v[46:47], v[66:67] op_sel_hi:[1,0]
	v_pk_mul_f32 v[44:45], v[44:45], v[66:67] op_sel_hi:[1,0]
	v_pk_mul_f32 v[42:43], v[42:43], v[66:67] op_sel_hi:[1,0]
	v_pk_mul_f32 v[40:41], v[40:41], v[66:67] op_sel_hi:[1,0]
	v_pk_mul_f32 v[38:39], v[38:39], v[66:67] op_sel_hi:[1,0]
	v_pk_mul_f32 v[36:37], v[36:37], v[66:67] op_sel_hi:[1,0]
	v_pk_mul_f32 v[34:35], v[34:35], v[66:67] op_sel_hi:[1,0]
	v_pk_mul_f32 v[32:33], v[32:33], v[66:67] op_sel_hi:[1,0]
	v_pk_mul_f32 v[30:31], v[30:31], v[66:67] op_sel_hi:[1,0]
	v_pk_mul_f32 v[28:29], v[28:29], v[66:67] op_sel_hi:[1,0]
	v_pk_mul_f32 v[26:27], v[26:27], v[66:67] op_sel_hi:[1,0]
	v_pk_mul_f32 v[24:25], v[24:25], v[66:67] op_sel_hi:[1,0]
	v_pk_mul_f32 v[22:23], v[22:23], v[66:67] op_sel_hi:[1,0]
	v_pk_mul_f32 v[20:21], v[20:21], v[66:67] op_sel_hi:[1,0]
	v_pk_mul_f32 v[18:19], v[18:19], v[66:67] op_sel_hi:[1,0]
	v_pk_mul_f32 v[16:17], v[16:17], v[66:67] op_sel_hi:[1,0]
	v_pk_add_f32 v[66:67], v[156:157], v[64:65]
	v_pk_mul_f32 v[64:65], v[156:157], v[64:65]
	s_nop 0
	v_mov_b32_e32 v67, v65
	v_sub_f32_e32 v64, v167, v66
	v_mov_b64_e32 v[156:157], v[66:67]
	v_mov_b32_e32 v65, v64
	v_mov_b32_e32 v66, v64
	v_mov_b32_e32 v67, v64
	v_mov_b32_e32 v68, v64
	v_mov_b32_e32 v69, v64
	v_mov_b32_e32 v70, v64
	v_mov_b32_e32 v71, v64
	v_mov_b32_e32 v72, v64
	v_mov_b32_e32 v73, v64
	v_mov_b32_e32 v74, v64
	v_mov_b32_e32 v75, v64
	v_mov_b32_e32 v76, v64
	v_mov_b32_e32 v77, v64
	v_mov_b32_e32 v78, v64
	v_mov_b32_e32 v79, v64

.LBB0_686:
	ds_read_b128 v[166:169], v84 offset:64
	ds_read_b128 v[170:173], v84 offset:96
	ds_read_b128 v[178:181], v84 offset:4672
	ds_read_b128 v[182:185], v84 offset:4704
	s_add_i32 s16, s91, s58
	s_add_i32 s4, s16, 64
	s_cmpk_lt_i32 s4, 0xff42
	s_cselect_b64 vcc, -1, 0
	s_cmpk_gt_i32 s4, 0x9e
	s_cselect_b64 s[4:5], -1, 0
	v_cndmask_b32_e64 v84, 0, v160, s[4:5]
	v_cndmask_b32_e32 v165, v84, v159, vcc
	v_sub_f32_e32 v84, v165, v156
	v_cmp_neq_f32_e64 s[4:5], v165, v142
	s_addk_i32 s16, 0xffa1
	s_cmp_lt_u32 s16, 0xfffffea3
	s_mov_b64 vcc, s[4:5]
	s_cbranch_vccz .Lattn_negm_keep_2
	v_mov_b32_e32 v79, v84
	v_mov_b32_e32 v78, v84
	v_mov_b32_e32 v77, v84
	v_mov_b32_e32 v76, v84
	v_mov_b32_e32 v75, v84
	v_mov_b32_e32 v74, v84
	v_mov_b32_e32 v73, v84
	v_mov_b32_e32 v72, v84
	v_mov_b32_e32 v71, v84
	v_mov_b32_e32 v70, v84
	v_mov_b32_e32 v69, v84
	v_mov_b32_e32 v68, v84
	v_mov_b32_e32 v67, v84
	v_mov_b32_e32 v66, v84
	v_mov_b32_e32 v65, v84
	v_mov_b32_e32 v64, v84
.Lattn_negm_keep_2:
	s_waitcnt lgkmcnt(0)
	s_nop 0
	v_mfma_f32_32x32x16_bf16 v[96:111], v[80:83], v[112:115], v[64:79]
	v_mfma_f32_32x32x16_bf16 v[80:95], v[136:139], v[112:115], v[64:79]
	v_mfma_f32_32x32x16_bf16 v[96:111], v[128:131], v[116:119], v[96:111]
	v_mfma_f32_32x32x16_bf16 v[80:95], v[132:135], v[116:119], v[80:95]
	v_mfma_f32_32x32x16_bf16 v[96:111], v[166:169], v[120:123], v[96:111]
	v_mfma_f32_32x32x16_bf16 v[80:95], v[178:181], v[120:123], v[80:95]
	v_mfma_f32_32x32x16_bf16 v[96:111], v[170:173], v[124:127], v[96:111]
	v_mfma_f32_32x32x16_bf16 v[80:95], v[182:185], v[124:127], v[80:95]
	s_cbranch_scc1 .LBB0_688
	v_add_u32_e32 v180, s58, v164
	v_max_i32_e32 v130, 0xffffff7f, v180
	v_add_u32_e32 v130, 0x81, v130
	s_add_i32 s80, 0, 0x20000
	v_min_u32_e32 v130, 0x100, v130
	v_lshl_add_u32 v132, v130, 2, s80
	v_max_i32_e32 v130, 0xffffff7e, v180
	v_add_u32_e32 v130, 0x82, v130
	v_max_i32_e32 v138, 0xffffff7b, v180
	v_min_u32_e32 v130, 0x100, v130
	v_add_u32_e32 v138, 0x85, v138
	v_max_i32_e32 v128, 0xffffff80, v180
	v_max_i32_e32 v129, 0xffffff60, v180
	v_max_i32_e32 v131, 0xffffff5f, v180
	v_max_i32_e32 v133, 0xffffff5e, v180
	v_lshl_add_u32 v134, v130, 2, s80
	v_max_i32_e32 v130, 0xffffff7d, v180
	v_max_i32_e32 v135, 0xffffff5d, v180
	v_min_u32_e32 v138, 0x100, v138
	v_add_u32_e32 v128, 0x80, v128
	v_add_u32_e32 v129, 0xa0, v129
	v_add_u32_e32 v131, 0xa1, v131
	v_add_u32_e32 v133, 0xa2, v133
	v_add_u32_e32 v130, 0x83, v130
	v_add_u32_e32 v135, 0xa3, v135
	v_lshl_add_u32 v166, v138, 2, s80
	v_max_i32_e32 v138, 0xffffff7a, v180
	v_min_u32_e32 v128, 0x100, v128
	v_min_u32_e32 v129, 0x100, v129
	v_min_u32_e32 v131, 0x100, v131
	v_min_u32_e32 v133, 0x100, v133
	v_min_u32_e32 v130, 0x100, v130
	v_min_u32_e32 v135, 0x100, v135
	v_add_u32_e32 v138, 0x86, v138
	v_max_i32_e32 v172, 0xffffff77, v180
	v_lshl_add_u32 v128, v128, 2, s80
	v_lshl_add_u32 v129, v129, 2, s80
	v_lshl_add_u32 v131, v131, 2, s80
	v_lshl_add_u32 v133, v133, 2, s80
	v_lshl_add_u32 v136, v130, 2, s80
	v_lshl_add_u32 v135, v135, 2, s80
	v_min_u32_e32 v138, 0x100, v138
	v_add_u32_e32 v172, 0x89, v172
	ds_read_b32 v128, v128
	ds_read_b32 v130, v129
	ds_read_b32 v129, v132
	ds_read_b32 v131, v131
	ds_read_b32 v132, v134
	ds_read_b32 v134, v133
	ds_read_b32 v133, v136
	ds_read_b32 v135, v135
	v_max_i32_e32 v136, 0xffffff7c, v180
	v_max_i32_e32 v137, 0xffffff5c, v180
	v_max_i32_e32 v139, 0xffffff5b, v180
	v_max_i32_e32 v167, 0xffffff5a, v180
	v_lshl_add_u32 v168, v138, 2, s80
	v_max_i32_e32 v138, 0xffffff79, v180
	v_max_i32_e32 v169, 0xffffff59, v180
	v_min_u32_e32 v172, 0x100, v172
	v_add_u32_e32 v136, 0x84, v136
	v_add_u32_e32 v137, 0xa4, v137
	v_add_u32_e32 v139, 0xa5, v139
	v_add_u32_e32 v167, 0xa6, v167
	v_add_u32_e32 v138, 0x87, v138
	v_add_u32_e32 v169, 0xa7, v169
	v_lshl_add_u32 v174, v172, 2, s80
	v_max_i32_e32 v172, 0xffffff76, v180
	v_min_u32_e32 v136, 0x100, v136
	v_min_u32_e32 v137, 0x100, v137
	v_min_u32_e32 v139, 0x100, v139
	v_min_u32_e32 v167, 0x100, v167
	v_min_u32_e32 v138, 0x100, v138
	v_min_u32_e32 v169, 0x100, v169
	v_add_u32_e32 v172, 0x8a, v172
	v_lshl_add_u32 v136, v136, 2, s80
	v_lshl_add_u32 v137, v137, 2, s80
	v_lshl_add_u32 v139, v139, 2, s80
	v_lshl_add_u32 v167, v167, 2, s80
	v_lshl_add_u32 v170, v138, 2, s80
	v_lshl_add_u32 v169, v169, 2, s80
	v_min_u32_e32 v172, 0x100, v172
	ds_read_b32 v136, v136
	ds_read_b32 v138, v137
	ds_read_b32 v137, v166
	ds_read_b32 v139, v139
	ds_read_b32 v166, v168
	ds_read_b32 v168, v167
	ds_read_b32 v167, v170
	ds_read_b32 v169, v169
	v_max_i32_e32 v170, 0xffffff78, v180
	v_max_i32_e32 v171, 0xffffff58, v180
	v_max_i32_e32 v173, 0xffffff57, v180
	v_max_i32_e32 v175, 0xffffff56, v180
	v_lshl_add_u32 v178, v172, 2, s80
	v_max_i32_e32 v172, 0xffffff75, v180
	v_max_i32_e32 v179, 0xffffff55, v180
	v_add_u32_e32 v170, 0x88, v170
	v_add_u32_e32 v171, 0xa8, v171
	v_add_u32_e32 v173, 0xa9, v173
	v_add_u32_e32 v175, 0xaa, v175
	v_add_u32_e32 v172, 0x8b, v172
	v_add_u32_e32 v179, 0xab, v179
	v_max_i32_e32 v184, 0xffffff53, v180
	v_max_i32_e32 v185, 0xffffff52, v180
	v_min_u32_e32 v170, 0x100, v170
	v_min_u32_e32 v171, 0x100, v171
	v_min_u32_e32 v173, 0x100, v173
	v_min_u32_e32 v175, 0x100, v175
	v_min_u32_e32 v172, 0x100, v172
	v_min_u32_e32 v179, 0x100, v179
	v_add_u32_e32 v184, 0xad, v184
	v_add_u32_e32 v185, 0xae, v185
	v_lshl_add_u32 v170, v170, 2, s80
	v_lshl_add_u32 v171, v171, 2, s80
	v_lshl_add_u32 v173, v173, 2, s80
	v_lshl_add_u32 v175, v175, 2, s80
	v_lshl_add_u32 v181, v172, 2, s80
	v_lshl_add_u32 v179, v179, 2, s80
	v_min_u32_e32 v184, 0x100, v184
	v_min_u32_e32 v185, 0x100, v185
	ds_read_b32 v170, v170
	ds_read_b32 v172, v171
	ds_read_b32 v171, v174
	ds_read_b32 v173, v173
	ds_read_b32 v174, v178
	ds_read_b32 v178, v175
	ds_read_b32 v175, v181
	ds_read_b32 v179, v179
	v_max_i32_e32 v181, 0xffffff74, v180
	v_max_i32_e32 v182, 0xffffff54, v180
	v_max_i32_e32 v183, 0xffffff73, v180
	v_lshl_add_u32 v188, v184, 2, s80
	v_max_i32_e32 v184, 0xffffff72, v180
	v_lshl_add_u32 v186, v185, 2, s80
	v_max_i32_e32 v185, 0xffffff71, v180
	v_max_i32_e32 v180, 0xffffff51, v180
	v_add_u32_e32 v181, 0x8c, v181
	v_add_u32_e32 v182, 0xac, v182
	v_add_u32_e32 v183, 0x8d, v183
	v_add_u32_e32 v184, 0x8e, v184
	v_add_u32_e32 v185, 0x8f, v185
	v_add_u32_e32 v180, 0xaf, v180
	v_min_u32_e32 v181, 0x100, v181
	v_min_u32_e32 v182, 0x100, v182
	v_min_u32_e32 v183, 0x100, v183
	v_min_u32_e32 v184, 0x100, v184
	v_min_u32_e32 v185, 0x100, v185
	v_min_u32_e32 v180, 0x100, v180
	v_lshl_add_u32 v181, v181, 2, s80
	v_lshl_add_u32 v182, v182, 2, s80
	v_lshl_add_u32 v183, v183, 2, s80
	v_lshl_add_u32 v184, v184, 2, s80
	v_lshl_add_u32 v185, v185, 2, s80
	v_lshl_add_u32 v187, v180, 2, s80
	ds_read_b32 v180, v181
	ds_read_b32 v182, v182
	ds_read_b32 v184, v184
	ds_read_b32 v185, v185
	ds_read_b32 v181, v183
	ds_read_b32 v187, v187
	ds_read_b32 v186, v186
	ds_read_b32 v183, v188
	s_waitcnt lgkmcnt(0)
	v_pk_add_f32 v[110:111], v[110:111], v[184:185]
	v_pk_add_f32 v[108:109], v[108:109], v[180:181]
	v_pk_add_f32 v[106:107], v[106:107], v[174:175]
	v_pk_add_f32 v[104:105], v[104:105], v[170:171]
	v_pk_add_f32 v[102:103], v[102:103], v[166:167]
	v_pk_add_f32 v[100:101], v[100:101], v[136:137]
	v_pk_add_f32 v[98:99], v[98:99], v[132:133]
	v_pk_add_f32 v[96:97], v[96:97], v[128:129]
	v_pk_add_f32 v[94:95], v[94:95], v[186:187]
	v_pk_add_f32 v[92:93], v[92:93], v[182:183]
	v_pk_add_f32 v[90:91], v[90:91], v[178:179]
	v_pk_add_f32 v[88:89], v[88:89], v[172:173]
	v_pk_add_f32 v[86:87], v[86:87], v[168:169]
	v_pk_add_f32 v[84:85], v[84:85], v[138:139]
	v_pk_add_f32 v[82:83], v[82:83], v[134:135]
	v_pk_add_f32 v[80:81], v[80:81], v[130:131]

.LBB0_700:
	s_add_i32 s56, s44, 0
	v_add3_u32 v84, s56, v162, v146
	ds_read_b128 v[80:83], v84
	ds_read_b128 v[128:131], v84 offset:32
	ds_read_b128 v[132:135], v84 offset:4608
	ds_read_b128 v[136:139], v84 offset:4640
	ds_read_b128 v[140:143], v84 offset:64
	ds_read_b128 v[168:171], v84 offset:96
	ds_read_b128 v[172:175], v84 offset:4672
	ds_read_b128 v[178:181], v84 offset:4704
	s_add_i32 s16, s27, s20
	s_add_i32 s4, s16, 64
	s_cmpk_lt_i32 s4, 0xff42
	s_cselect_b64 vcc, -1, 0
	s_cmpk_gt_i32 s4, 0x9e
	s_cselect_b64 s[4:5], -1, 0
	v_cndmask_b32_e64 v84, 0, v160, s[4:5]
	v_cndmask_b32_e32 v167, v84, v159, vcc
	v_sub_f32_e32 v84, v167, v156
	v_cmp_neq_f32_e64 s[4:5], v167, v163
	s_addk_i32 s16, 0xffa1
	s_cmp_lt_u32 s16, 0xfffffea3
	s_mov_b64 vcc, s[4:5]
	s_cbranch_vccz .Lattn_negm_keep_3
	v_mov_b32_e32 v79, v84
	v_mov_b32_e32 v78, v84
	v_mov_b32_e32 v77, v84
	v_mov_b32_e32 v76, v84
	v_mov_b32_e32 v75, v84
	v_mov_b32_e32 v74, v84
	v_mov_b32_e32 v73, v84
	v_mov_b32_e32 v72, v84
	v_mov_b32_e32 v71, v84
	v_mov_b32_e32 v70, v84
	v_mov_b32_e32 v69, v84
	v_mov_b32_e32 v68, v84
	v_mov_b32_e32 v67, v84
	v_mov_b32_e32 v66, v84
	v_mov_b32_e32 v65, v84
	v_mov_b32_e32 v64, v84
.Lattn_negm_keep_3:
	s_waitcnt lgkmcnt(0)
	s_nop 0
	v_mfma_f32_32x32x16_bf16 v[96:111], v[80:83], v[112:115], v[64:79]
	v_mfma_f32_32x32x16_bf16 v[80:95], v[132:135], v[112:115], v[64:79]
	v_mfma_f32_32x32x16_bf16 v[96:111], v[128:131], v[116:119], v[96:111]
	v_mfma_f32_32x32x16_bf16 v[80:95], v[136:139], v[116:119], v[80:95]
	v_mfma_f32_32x32x16_bf16 v[96:111], v[140:143], v[120:123], v[96:111]
	v_mfma_f32_32x32x16_bf16 v[80:95], v[172:175], v[120:123], v[80:95]
	v_mfma_f32_32x32x16_bf16 v[96:111], v[168:171], v[124:127], v[96:111]
	v_mfma_f32_32x32x16_bf16 v[80:95], v[178:181], v[124:127], v[80:95]
	s_cbranch_scc1 .LBB0_702
	v_add_u32_e32 v178, s20, v166
	v_max_i32_e32 v130, 0xffffff7f, v178
	v_add_u32_e32 v130, 0x81, v130
	s_add_i32 s57, 0, 0x20000
	v_min_u32_e32 v130, 0x100, v130
	v_lshl_add_u32 v132, v130, 2, s57
	v_max_i32_e32 v130, 0xffffff7e, v178
	v_add_u32_e32 v130, 0x82, v130
	v_max_i32_e32 v138, 0xffffff7b, v178
	v_min_u32_e32 v130, 0x100, v130
	v_add_u32_e32 v138, 0x85, v138
	v_max_i32_e32 v128, 0xffffff80, v178
	v_max_i32_e32 v129, 0xffffff60, v178
	v_max_i32_e32 v131, 0xffffff5f, v178
	v_max_i32_e32 v133, 0xffffff5e, v178
	v_lshl_add_u32 v134, v130, 2, s57
	v_max_i32_e32 v130, 0xffffff7d, v178
	v_max_i32_e32 v135, 0xffffff5d, v178
	v_min_u32_e32 v138, 0x100, v138
	v_add_u32_e32 v128, 0x80, v128
	v_add_u32_e32 v129, 0xa0, v129
	v_add_u32_e32 v131, 0xa1, v131
	v_add_u32_e32 v133, 0xa2, v133
	v_add_u32_e32 v130, 0x83, v130
	v_add_u32_e32 v135, 0xa3, v135
	v_lshl_add_u32 v140, v138, 2, s57
	v_max_i32_e32 v138, 0xffffff7a, v178
	v_min_u32_e32 v128, 0x100, v128
	v_min_u32_e32 v129, 0x100, v129
	v_min_u32_e32 v131, 0x100, v131
	v_min_u32_e32 v133, 0x100, v133
	v_min_u32_e32 v130, 0x100, v130
	v_min_u32_e32 v135, 0x100, v135
	v_add_u32_e32 v138, 0x86, v138
	v_max_i32_e32 v170, 0xffffff77, v178
	v_lshl_add_u32 v128, v128, 2, s57
	v_lshl_add_u32 v129, v129, 2, s57
	v_lshl_add_u32 v131, v131, 2, s57
	v_lshl_add_u32 v133, v133, 2, s57
	v_lshl_add_u32 v136, v130, 2, s57
	v_lshl_add_u32 v135, v135, 2, s57
	v_min_u32_e32 v138, 0x100, v138
	v_add_u32_e32 v170, 0x89, v170
	ds_read_b32 v128, v128
	ds_read_b32 v130, v129
	ds_read_b32 v129, v132
	ds_read_b32 v131, v131
	ds_read_b32 v132, v134
	ds_read_b32 v134, v133
	ds_read_b32 v133, v136
	ds_read_b32 v135, v135
	v_max_i32_e32 v136, 0xffffff7c, v178
	v_max_i32_e32 v137, 0xffffff5c, v178
	v_max_i32_e32 v139, 0xffffff5b, v178
	v_max_i32_e32 v141, 0xffffff5a, v178
	v_lshl_add_u32 v142, v138, 2, s57
	v_max_i32_e32 v138, 0xffffff79, v178
	v_max_i32_e32 v143, 0xffffff59, v178
	v_min_u32_e32 v170, 0x100, v170
	v_add_u32_e32 v136, 0x84, v136
	v_add_u32_e32 v137, 0xa4, v137
	v_add_u32_e32 v139, 0xa5, v139
	v_add_u32_e32 v141, 0xa6, v141
	v_add_u32_e32 v138, 0x87, v138
	v_add_u32_e32 v143, 0xa7, v143
	v_lshl_add_u32 v172, v170, 2, s57
	v_max_i32_e32 v170, 0xffffff76, v178
	v_min_u32_e32 v136, 0x100, v136
	v_min_u32_e32 v137, 0x100, v137
	v_min_u32_e32 v139, 0x100, v139
	v_min_u32_e32 v141, 0x100, v141
	v_min_u32_e32 v138, 0x100, v138
	v_min_u32_e32 v143, 0x100, v143
	v_add_u32_e32 v170, 0x8a, v170
	v_lshl_add_u32 v136, v136, 2, s57
	v_lshl_add_u32 v137, v137, 2, s57
	v_lshl_add_u32 v139, v139, 2, s57
	v_lshl_add_u32 v141, v141, 2, s57
	v_lshl_add_u32 v168, v138, 2, s57
	v_lshl_add_u32 v143, v143, 2, s57
	v_min_u32_e32 v170, 0x100, v170
	ds_read_b32 v136, v136
	ds_read_b32 v138, v137
	ds_read_b32 v137, v140
	ds_read_b32 v139, v139
	ds_read_b32 v140, v142
	ds_read_b32 v142, v141
	ds_read_b32 v141, v168
	ds_read_b32 v143, v143
	v_max_i32_e32 v168, 0xffffff78, v178
	v_max_i32_e32 v169, 0xffffff58, v178
	v_max_i32_e32 v171, 0xffffff57, v178
	v_max_i32_e32 v173, 0xffffff56, v178
	v_lshl_add_u32 v174, v170, 2, s57
	v_max_i32_e32 v170, 0xffffff75, v178
	v_max_i32_e32 v175, 0xffffff55, v178
	v_add_u32_e32 v168, 0x88, v168
	v_add_u32_e32 v169, 0xa8, v169
	v_add_u32_e32 v171, 0xa9, v171
	v_add_u32_e32 v173, 0xaa, v173
	v_add_u32_e32 v170, 0x8b, v170
	v_add_u32_e32 v175, 0xab, v175
	v_max_i32_e32 v182, 0xffffff53, v178
	v_max_i32_e32 v183, 0xffffff52, v178
	v_min_u32_e32 v168, 0x100, v168
	v_min_u32_e32 v169, 0x100, v169
	v_min_u32_e32 v171, 0x100, v171
	v_min_u32_e32 v173, 0x100, v173
	v_min_u32_e32 v170, 0x100, v170
	v_min_u32_e32 v175, 0x100, v175
	v_add_u32_e32 v182, 0xad, v182
	v_add_u32_e32 v183, 0xae, v183
	v_lshl_add_u32 v168, v168, 2, s57
	v_lshl_add_u32 v169, v169, 2, s57
	v_lshl_add_u32 v171, v171, 2, s57
	v_lshl_add_u32 v173, v173, 2, s57
	v_lshl_add_u32 v179, v170, 2, s57
	v_lshl_add_u32 v175, v175, 2, s57
	v_min_u32_e32 v182, 0x100, v182
	v_min_u32_e32 v183, 0x100, v183
	ds_read_b32 v168, v168
	ds_read_b32 v170, v169
	ds_read_b32 v169, v172
	ds_read_b32 v171, v171
	ds_read_b32 v172, v174
	ds_read_b32 v174, v173
	ds_read_b32 v173, v179
	ds_read_b32 v175, v175
	v_max_i32_e32 v179, 0xffffff74, v178
	v_max_i32_e32 v180, 0xffffff54, v178
	v_max_i32_e32 v181, 0xffffff73, v178
	v_lshl_add_u32 v186, v182, 2, s57
	v_max_i32_e32 v182, 0xffffff72, v178
	v_lshl_add_u32 v184, v183, 2, s57
	v_max_i32_e32 v183, 0xffffff71, v178
	v_max_i32_e32 v178, 0xffffff51, v178
	v_add_u32_e32 v179, 0x8c, v179
	v_add_u32_e32 v180, 0xac, v180
	v_add_u32_e32 v181, 0x8d, v181
	v_add_u32_e32 v182, 0x8e, v182
	v_add_u32_e32 v183, 0x8f, v183
	v_add_u32_e32 v178, 0xaf, v178
	v_min_u32_e32 v179, 0x100, v179
	v_min_u32_e32 v180, 0x100, v180
	v_min_u32_e32 v181, 0x100, v181
	v_min_u32_e32 v182, 0x100, v182
	v_min_u32_e32 v183, 0x100, v183
	v_min_u32_e32 v178, 0x100, v178
	v_lshl_add_u32 v179, v179, 2, s57
	v_lshl_add_u32 v180, v180, 2, s57
	v_lshl_add_u32 v181, v181, 2, s57
	v_lshl_add_u32 v182, v182, 2, s57
	v_lshl_add_u32 v183, v183, 2, s57
	v_lshl_add_u32 v185, v178, 2, s57
	ds_read_b32 v178, v179
	ds_read_b32 v180, v180
	ds_read_b32 v182, v182
	ds_read_b32 v183, v183
	ds_read_b32 v179, v181
	ds_read_b32 v185, v185
	ds_read_b32 v184, v184
	ds_read_b32 v181, v186
	s_waitcnt lgkmcnt(0)
	v_pk_add_f32 v[110:111], v[110:111], v[182:183]
	v_pk_add_f32 v[108:109], v[108:109], v[178:179]
	v_pk_add_f32 v[106:107], v[106:107], v[172:173]
	v_pk_add_f32 v[104:105], v[104:105], v[168:169]
	v_pk_add_f32 v[102:103], v[102:103], v[140:141]
	v_pk_add_f32 v[100:101], v[100:101], v[136:137]
	v_pk_add_f32 v[98:99], v[98:99], v[132:133]
	v_pk_add_f32 v[96:97], v[96:97], v[128:129]
	v_pk_add_f32 v[94:95], v[94:95], v[184:185]
	v_pk_add_f32 v[92:93], v[92:93], v[180:181]
	v_pk_add_f32 v[90:91], v[90:91], v[174:175]
	v_pk_add_f32 v[88:89], v[88:89], v[170:171]
	v_pk_add_f32 v[86:87], v[86:87], v[142:143]
	v_pk_add_f32 v[84:85], v[84:85], v[138:139]
	v_pk_add_f32 v[82:83], v[82:83], v[134:135]
	v_pk_add_f32 v[80:81], v[80:81], v[130:131]
